# v57 + attention (executing no-shift variant): transposed V reads of the PV block issued ahead with counted waits
# speedup vs baseline: 1.0075x; 1.0075x over previous
.LBB0_349:
	v_exp_f32_e32 v198, v112
	v_exp_f32_e32 v199, v80
	v_exp_f32_e32 v202, v113
	v_exp_f32_e32 v203, v81
	v_exp_f32_e32 v204, v114
	v_exp_f32_e32 v205, v82
	v_exp_f32_e32 v206, v115
	v_exp_f32_e32 v207, v83
	v_exp_f32_e32 v208, v116
	v_exp_f32_e32 v209, v84
	v_exp_f32_e32 v211, v85
	v_pk_add_f32 v[84:85], v[198:199], 0 op_sel_hi:[1,0]
	v_exp_f32_e32 v210, v117
	v_pk_add_f32 v[84:85], v[202:203], v[84:85]
	v_exp_f32_e32 v212, v118
	v_exp_f32_e32 v213, v86
	v_pk_add_f32 v[84:85], v[204:205], v[84:85]
	v_exp_f32_e32 v214, v119
	v_exp_f32_e32 v215, v87
	v_pk_add_f32 v[84:85], v[206:207], v[84:85]
	v_exp_f32_e32 v120, v120
	v_exp_f32_e32 v216, v121
	v_exp_f32_e32 v121, v88
	v_pk_add_f32 v[84:85], v[208:209], v[84:85]
	v_exp_f32_e32 v217, v89
	v_pk_add_f32 v[84:85], v[210:211], v[84:85]
	v_exp_f32_e32 v122, v122
	v_exp_f32_e32 v218, v123
	v_exp_f32_e32 v123, v90
	v_pk_add_f32 v[84:85], v[212:213], v[84:85]
	v_exp_f32_e32 v219, v91
	v_pk_add_f32 v[84:85], v[214:215], v[84:85]
	v_exp_f32_e32 v124, v124
	v_exp_f32_e32 v220, v125
	v_pk_add_f32 v[84:85], v[120:121], v[84:85]
	v_exp_f32_e32 v125, v92
	v_pk_add_f32 v[84:85], v[216:217], v[84:85]
	v_exp_f32_e32 v221, v93
	v_exp_f32_e32 v126, v126
	v_exp_f32_e32 v222, v127
	v_pk_add_f32 v[88:89], v[122:123], v[84:85]
	v_exp_f32_e32 v127, v94
	v_exp_f32_e32 v223, v95
	v_exp_f32_e32 v225, v64
	v_exp_f32_e32 v227, v65
	v_pk_add_f32 v[64:65], v[218:219], v[88:89]
	v_exp_f32_e32 v224, v96
	v_pk_add_f32 v[64:65], v[124:125], v[64:65]
	v_exp_f32_e32 v226, v97
	v_pk_add_f32 v[64:65], v[220:221], v[64:65]
	v_exp_f32_e32 v228, v98
	v_exp_f32_e32 v229, v66
	v_pk_add_f32 v[64:65], v[126:127], v[64:65]
	v_exp_f32_e32 v230, v99
	v_exp_f32_e32 v231, v67
	v_pk_add_f32 v[64:65], v[222:223], v[64:65]
	v_exp_f32_e32 v232, v100
	v_exp_f32_e32 v233, v68
	v_pk_add_f32 v[64:65], v[224:225], v[64:65]
	v_exp_f32_e32 v234, v101
	v_exp_f32_e32 v235, v69
	v_pk_add_f32 v[64:65], v[226:227], v[64:65]
	v_exp_f32_e32 v236, v102
	v_pk_add_f32 v[64:65], v[228:229], v[64:65]
	v_exp_f32_e32 v237, v70
	v_exp_f32_e32 v238, v103
	v_pk_add_f32 v[64:65], v[230:231], v[64:65]
	v_exp_f32_e32 v239, v71
	v_exp_f32_e32 v104, v104
	v_exp_f32_e32 v240, v105
	v_pk_add_f32 v[64:65], v[232:233], v[64:65]
	v_exp_f32_e32 v105, v72
	v_pk_add_f32 v[68:69], v[234:235], v[64:65]
	v_exp_f32_e32 v241, v73
	v_exp_f32_e32 v106, v106
	v_exp_f32_e32 v242, v107
	v_exp_f32_e32 v107, v74
	v_pk_add_f32 v[68:69], v[236:237], v[68:69]
	v_exp_f32_e32 v243, v75
	v_pk_add_f32 v[68:69], v[238:239], v[68:69]
	v_exp_f32_e32 v108, v108
	v_exp_f32_e32 v244, v109
	v_exp_f32_e32 v109, v76
	v_pk_add_f32 v[68:69], v[104:105], v[68:69]
	v_exp_f32_e32 v245, v77
	v_pk_add_f32 v[68:69], v[240:241], v[68:69]
	v_exp_f32_e32 v110, v110
	v_exp_f32_e32 v246, v111
	v_exp_f32_e32 v111, v78
	v_pk_add_f32 v[68:69], v[106:107], v[68:69]
	v_exp_f32_e32 v247, v79
	v_pk_add_f32 v[68:69], v[242:243], v[68:69]
	v_cvt_pk_bf16_f32 v116, v198, v202
	v_cvt_pk_bf16_f32 v117, v204, v206
	v_cvt_pk_bf16_f32 v118, v208, v210
	v_cvt_pk_bf16_f32 v119, v212, v214
	v_cvt_pk_bf16_f32 v112, v120, v216
	s_nop 0
	v_pk_add_f32 v[68:69], v[108:109], v[68:69]
	v_cvt_pk_bf16_f32 v113, v122, v218
	v_cvt_pk_bf16_f32 v114, v124, v220
	v_cvt_pk_bf16_f32 v115, v126, v222
	v_cvt_pk_bf16_f32 v100, v224, v226
	v_cvt_pk_bf16_f32 v101, v228, v230
	s_nop 0
	v_pk_add_f32 v[68:69], v[244:245], v[68:69]
	v_cvt_pk_bf16_f32 v102, v232, v234
	v_cvt_pk_bf16_f32 v103, v236, v238
	v_cvt_pk_bf16_f32 v96, v104, v240
	v_cvt_pk_bf16_f32 v97, v106, v242
	v_cvt_pk_bf16_f32 v98, v108, v244
	s_nop 0
	v_pk_add_f32 v[68:69], v[110:111], v[68:69]
	v_cvt_pk_bf16_f32 v99, v110, v246
	v_cvt_pk_bf16_f32 v80, v199, v203
	v_cvt_pk_bf16_f32 v81, v205, v207
	v_cvt_pk_bf16_f32 v82, v209, v211
	v_cvt_pk_bf16_f32 v83, v213, v215
	s_nop 0
	v_pk_add_f32 v[72:73], v[246:247], v[68:69]
	v_cvt_pk_bf16_f32 v84, v121, v217
	v_cvt_pk_bf16_f32 v85, v123, v219
	v_cvt_pk_bf16_f32 v86, v125, v221
	v_cvt_pk_bf16_f32 v87, v127, v223
	v_cvt_pk_bf16_f32 v64, v225, v227
	s_nop 0
	v_pk_add_f32 v[190:191], v[190:191], v[72:73]
	v_cvt_pk_bf16_f32 v65, v229, v231
	v_cvt_pk_bf16_f32 v66, v233, v235
	v_cvt_pk_bf16_f32 v67, v237, v239
	v_cvt_pk_bf16_f32 v68, v105, v241
	v_cvt_pk_bf16_f32 v69, v107, v243
	v_cvt_pk_bf16_f32 v70, v109, v245
	v_cvt_pk_bf16_f32 v71, v111, v247
	ds_read_b64_tr_b16 v[206:207], v195 offset:9216
	ds_read_b64_tr_b16 v[208:209], v195 offset:10368
	ds_read_b64_tr_b16 v[210:211], v195 offset:9280
	ds_read_b64_tr_b16 v[212:213], v195 offset:10432
	ds_read_b64_tr_b16 v[214:215], v195 offset:11520
	ds_read_b64_tr_b16 v[216:217], v195 offset:12672
	ds_read_b64_tr_b16 v[218:219], v195 offset:11584
	ds_read_b64_tr_b16 v[220:221], v195 offset:12736
	ds_read_b64_tr_b16 v[222:223], v195 offset:13824
	ds_read_b64_tr_b16 v[224:225], v195 offset:14976
	ds_read_b64_tr_b16 v[226:227], v195 offset:13888
	ds_read_b64_tr_b16 v[228:229], v195 offset:15040
	s_waitcnt lgkmcnt(10)
	v_mfma_f32_32x32x16_bf16 v[48:63], v[206:209], v[116:119], v[48:63]
	v_mfma_f32_32x32x16_bf16 v[16:31], v[206:209], v[80:83], v[16:31]
	ds_read_b64_tr_b16 v[230:231], v195 offset:16128
	ds_read_b64_tr_b16 v[232:233], v195 offset:17280
	s_waitcnt lgkmcnt(10)
	v_mfma_f32_32x32x16_bf16 v[32:47], v[210:213], v[116:119], v[32:47]
	v_mfma_f32_32x32x16_bf16 v[0:15], v[210:213], v[80:83], v[0:15]
	ds_read_b64_tr_b16 v[234:235], v195 offset:16192
	ds_read_b64_tr_b16 v[236:237], v195 offset:17344
	s_waitcnt lgkmcnt(10)
	v_mfma_f32_32x32x16_bf16 v[48:63], v[214:217], v[112:115], v[48:63]
	v_mfma_f32_32x32x16_bf16 v[16:31], v[214:217], v[84:87], v[16:31]
	s_waitcnt lgkmcnt(8)
	v_mfma_f32_32x32x16_bf16 v[32:47], v[218:221], v[112:115], v[32:47]
	v_mfma_f32_32x32x16_bf16 v[0:15], v[218:221], v[84:87], v[0:15]
	s_waitcnt lgkmcnt(6)
	v_mfma_f32_32x32x16_bf16 v[48:63], v[222:225], v[100:103], v[48:63]
	v_mfma_f32_32x32x16_bf16 v[16:31], v[222:225], v[64:67], v[16:31]
	s_waitcnt lgkmcnt(4)
	v_mfma_f32_32x32x16_bf16 v[0:15], v[226:229], v[64:67], v[0:15]
	v_mfma_f32_32x32x16_bf16 v[32:47], v[226:229], v[100:103], v[32:47]
	s_waitcnt lgkmcnt(2)
	v_mfma_f32_32x32x16_bf16 v[48:63], v[230:233], v[96:99], v[48:63]
	v_mfma_f32_32x32x16_bf16 v[16:31], v[230:233], v[68:71], v[16:31]
	s_waitcnt lgkmcnt(0)
	v_mfma_f32_32x32x16_bf16 v[32:47], v[234:237], v[96:99], v[32:47]
	v_mfma_f32_32x32x16_bf16 v[0:15], v[234:237], v[68:71], v[0:15]
